# retention core: next chunk's V tile requested right after this chunk's V tile is consumed (own registers v[90:93]), exact steady-state vmcnt waits with an extra first-chunk wait; drain waits at GLA un
# baseline (speedup 1.0000x reference)
; template <int DK, int DVS, bool RET> ...
;     ...
;     __syncthreads();
; __global__ void __launch_bounds__(512) mk_fwd(Params P) {
;     ...
;             for (int L = bid; L < 256; L += G) {
;                 const int slice = L & 3, dir = (L >> 2) & 1, hh = (L >> 3) & 7, bq = L >> 6;
;                 gla_unit<128, 32, false>(lds, bq, hh, dir, slice, Qb, nullptr, Vb, LF, dir ? OB : OF, 0.f, 1024, hh * 128 + slice * 32, tid);
;             }
.LBB0_51:
	s_waitcnt vmcnt(0)
	s_add_i32 s49, s49, s80
	s_cmpk_gt_i32 s49, 0xff
	s_barrier
	s_cbranch_scc1 .LBB0_58

; #define LAS __attribute__((address_space(3)))
; template <int DK, int DVS, bool RET> ...
;     ...
;     unsigned aQD = (unsigned)(uintptr_t)(LAS unsigned char*)lds, aKD = aQD + 64 * LK * 2, aSTB = aKD + 64 * LK * 2, aVI = aSTB + DVS * LK * 2,
;              aAT = aVI + 64 * LV * 2, aEL = aAT + 64 * LS * 2, aTOT = aEL + DK * 4;
;     asm volatile("" : "+s"(aQD), "+s"(aVI), "+s"(aAT), "+s"(aEL), "+s"(aTOT), "+s"(aKD), "+s"(aSTB));
;     LAS bf16_t* QD = (LAS bf16_t*)(uintptr_t)aQD; LAS bf16_t* VI = (LAS bf16_t*)(uintptr_t)aVI; LAS bf16_t* AT = (LAS bf16_t*)(uintptr_t)aAT;
;     LAS float* EL = (LAS float*)(uintptr_t)aEL; LAS float* TOT = (LAS float*)(uintptr_t)aTOT;
;     LAS bf16_t* KD = (LAS bf16_t*)(uintptr_t)aKD; LAS bf16_t* STB = (LAS bf16_t*)(uintptr_t)aSTB;
;     static_assert(2 * 64 * LK * 2 + DVS * LK * 2 + 64 * LV * 2 + 64 * LS * 2 + DK * 4 + 2048 <= 159744, "GLA LDS map");
;     const int wid = tid >> 6, lane = tid & 63, l16 = lane & 15, quad = lane >> 4;
;     const int tr = wid >> 1, tv = wid / WPV, kt0 = (wid % WPV) * TPW;
;     const int vtr = (int)aVI + (8 * quad + (l16 >> 2)) * (LV * 2) + 8 * (lane & 3);
;     const int ktr = (int)aKD + (8 * quad + (l16 >> 2)) * (LK * 2) + 8 * (lane & 3);
; __global__ void __launch_bounds__(512) mk_fwd(Params P) {
;     ...
;             for (int L = bid; L < 256; L += G) {
;                 const int slice = L & 7, dir = (L >> 3) & 1, hh = (L >> 4) & 3, bq = L >> 6;
;                 const float lg = __logf(1.f - exp2f(-P.in[16][dir * 4 + hh]));
;                 gla_unit<256, 64, true>(lds, bq, hh, dir, slice, Qb, Kb, Vb, nullptr, dir ? OB : OF, lg, 2048, hh * 512 + slice * 64, tid);
.LBB0_68:
	s_waitcnt vmcnt(0)
	s_add_i32 s3, s3, s80
	s_cmpk_gt_i32 s3, 0xff
	s_mov_b32 s47, 0x16969000
	s_barrier
	s_cbranch_scc1 .LBB0_75
.LBB0_69:
	s_bfe_u32 s28, s3, 0x10003
	s_bfe_u32 s24, s3, 0x20004
	s_lshl_b32 s22, s24, 2
	s_lshl_b32 s23, s28, 4
	s_or_b32 s22, s23, s22
	v_mov_b32_e32 v0, s22
	v_readlane_b32 s22, v254, 25
	v_readlane_b32 s23, v254, 26
	s_load_dwordx2 s[22:23], s[22:23], 0x80
	v_readlane_b32 s46, v254, 9
	v_readlane_b32 s29, v254, 4
	s_mov_b32 s30, s37
	v_readlane_b32 s41, v254, 6
	s_waitcnt lgkmcnt(0)
	global_load_dword v1, v0, s[22:23]
	s_ashr_i32 s22, s3, 6
	v_readlane_b32 s23, v254, 7
	v_readlane_b32 s45, v254, 8
	v_readlane_b32 s40, v254, 5
	s_mul_hi_i32 s43, s22, 0x1100
	s_mul_i32 s44, s22, 0x1100
	s_mov_b32 s22, 0x42fc0000
	s_bfe_i32 s25, s3, 0x10003
	v_add_u32_e32 v37, s29, v116
	v_add3_u32 v172, s29, v120, v78
	v_lshlrev_b32_e32 v36, 1, v69
	v_mov_b32_e32 v3, s43
	v_add_u32_e32 v38, s30, v36
	v_add_u32_e32 v40, s30, v170
	v_lshlrev_b64 v[86:87], 1, v[70:71]
	v_lshlrev_b64 v[88:89], 1, v[72:73]
	v_lshlrev_b64 v[90:91], 1, v[74:75]
	v_lshlrev_b64 v[92:93], 1, v[76:77]
	v_add_u32_e32 v41, s45, v170
	v_lshlrev_b32_e32 v49, 1, v70
	s_mov_b32 s31, s37
	v_add_u32_e32 v178, v40, v49
	v_add_u32_e32 v179, v41, v49
	v_lshlrev_b32_e32 v49, 1, v72
	v_lshlrev_b32_e32 v144, 1, v68
	v_add_u32_e32 v180, v40, v49
	v_add_u32_e32 v181, v41, v49
	v_lshlrev_b32_e32 v49, 1, v74
	v_add_u32_e32 v39, s46, v144
	v_add_u32_e32 v182, v40, v49
	v_add_u32_e32 v183, v41, v49
	v_lshlrev_b32_e32 v49, 1, v76
	v_mov_b32_e32 v0, 0
	v_add3_u32 v174, s45, v123, v36
	v_add_u32_e32 v175, s46, v36
	v_add3_u32 v176, s40, v125, v36
	v_lshl_add_u32 v36, v68, 2, s41
	v_add_u32_e32 v42, v39, v129
	v_add_u32_e32 v43, v39, v131
	v_add_u32_e32 v44, v39, v132
	v_add_u32_e32 v45, v39, v133
	v_add_u32_e32 v46, v39, v134
	v_add_u32_e32 v47, v39, v135
	v_add_u32_e32 v48, v39, v136
	v_add_u32_e32 v39, v39, v137
	v_add_u32_e32 v184, v40, v49
	v_lshlrev_b32_e32 v40, 1, v122
	v_mov_b32_e32 v83, v145
	v_mov_b32_e32 v85, v145
	s_mov_b32 s42, 0
	v_mov_b32_e32 v95, s43
	v_lshl_add_u32 v171, v118, 2, s41
	v_add_u32_e32 v177, v37, v128
	v_add_u32_e32 v185, v41, v49
	v_add3_u32 v199, s40, v138, v40
	v_add3_u32 v200, s40, v140, v40
	v_add3_u32 v201, s40, v142, v40
	v_add3_u32 v202, s40, v147, v40
	v_add_u32_e32 v203, v37, v151
	v_add_u32_e32 v210, v42, v130
	v_add_u32_e32 v211, v43, v130
	v_add_u32_e32 v212, v44, v130
	v_add_u32_e32 v213, v45, v130
	v_add_u32_e32 v214, v46, v130
	v_add_u32_e32 v215, v47, v130
	v_add_u32_e32 v216, v48, v130
	v_add_u32_e32 v217, v39, v130
	v_add_u32_e32 v218, v38, v121
	v_add_u32_e32 v219, v175, v155
	v_add_u32_e32 v220, v36, v162
	v_add_u32_e32 v221, v36, v163
	v_add_u32_e32 v222, v36, v164
	v_add_u32_e32 v223, v36, v165
	v_add_u32_e32 v224, v36, v166
	v_add_u32_e32 v225, v36, v167
	v_add_u32_e32 v226, v36, v168
	v_add_u32_e32 v227, v36, v169
	v_mov_b32_e32 v36, v0
	s_waitcnt vmcnt(0)
; #define GAS __attribute__((address_space(1)))
; __device__ __forceinline__ bf16_t f2bf(float x) { return (bf16_t)(cvt_pk_bf16(x, x) & 0xffffu); }
; #define GLA_BAR() do { asm volatile("s_waitcnt lgkmcnt(0)" ::: "memory"); __builtin_amdgcn_s_barrier(); asm volatile("" ::: "memory"); } while (0)
; template <int DK, int DVS, bool RET> ...
;     ...
;     bf16x8 qv[NQV], kv[NQV]; float lc[NLC]; bf16_t qr[NLC]; vvec_t vraw;
;     const int kx = tid % DK, pg = tid / DK;
;     const GAS bf16_t* Qg = (const GAS bf16_t*)Q; const GAS bf16_t* Kg = (const GAS bf16_t*)Kp; const GAS float* LFg = (const GAS float*)LF; const GAS bf16_t* Vg = (const GAS bf16_t*)V;
;     ...
;     GLA_LOAD(0);
;     for (int step = 0; step < 68; ++step) {
;         const int cidx = dir ? (step < 4 ? 3 - step : 71 - step) : step;
;         const long R0 = (long)b * TB + cidx * 64;
;         GLA_BAR();
;         {
; #pragma unroll
;             for (int t = 0; t < TPW; ++t)
; #pragma unroll
;                 for (int j = 0; j < 4; ++j) STB[(tv * 16 + quad * 4 + j) * LK + (kt0 + t) * 16 + l16] = f2bf(st[t][j]);
;             { const int p = tid >> 3, vg = tid & 7; const long row = R0 + (dir ? 63 - p : p); vraw = *(const GAS vvec_t*)(Vg + row * ldv + vcol0 + vg * VPT); }
	v_cmp_lt_f32_e64 s[22:23], s22, v1
	v_mov_b32_e32 v38, v0
	v_mov_b32_e32 v39, v0
	v_cndmask_b32_e64 v2, 0, v195, s[22:23]
	v_sub_f32_e32 v1, v2, v1
	v_exp_f32_e32 v1, v1
	s_and_b64 s[22:23], s[22:23], exec
	s_cselect_b32 s22, 0xffffffc0, 0
	v_xor_b32_e32 v2, 63, v148
	v_ldexp_f32 v1, v1, s22
	v_sub_f32_e32 v1, 1.0, v1
	v_cmp_gt_f32_e64 s[22:23], s53, v1
	v_mov_b32_e32 v44, v0
	v_mov_b32_e32 v45, v0
	v_cndmask_b32_e64 v6, 0, v196, s[22:23]
	s_and_b64 s[22:23], s[22:23], exec
	s_cselect_b32 s22, 32, 0
	s_cmp_eq_u32 s28, 0
	v_ldexp_f32 v1, v1, s22
	s_cselect_b64 s[22:23], -1, 0
	v_log_f32_e32 v1, v1
	s_and_b64 s[28:29], s[22:23], exec
	s_cselect_b32 s28, s47, 0x1ad69000
	s_add_u32 s47, s0, s28
	v_cndmask_b32_e64 v2, v2, v148, s[22:23]
	s_addc_u32 s48, s1, 0
	s_and_b32 s25, s25, 0xc0
	s_lshl_b32 s28, s3, 7
	v_or_b32_e32 v94, s44, v2
	v_mul_f32_e32 v4, 0x3f317217, v1
	v_or_b32_e32 v2, s25, v2
	s_and_b32 s25, s28, 0x380
	s_mov_b32 s28, 0x3f317217
	s_lshl_b32 s36, s24, 9
	s_lshl_b32 s24, s24, 10
	v_fma_f32 v7, v1, s28, -v4
	v_or_b32_e32 v2, s44, v2
	s_or_b32 s30, s24, s25
	v_fmac_f32_e32 v7, 0x3377d1cf, v1
	v_lshlrev_b64 v[2:3], 11, v[2:3]
	s_mov_b32 s24, 0x7f800000
	v_fmac_f32_e32 v7, 0x3f317217, v1
	v_lshl_add_u64 v[4:5], s[90:91], 0, v[2:3]
	v_lshl_add_u64 v[2:3], s[26:27], 0, v[2:3]
	v_cmp_lt_f32_e64 s[24:25], |v1|, s24
	v_lshl_add_u64 v[4:5], v[4:5], 0, s[36:37]
	v_lshl_add_u64 v[2:3], v[2:3], 0, s[36:37]
	v_cndmask_b32_e64 v1, v1, v7, s[24:25]
	v_sub_f32_e32 v1, v1, v6
	v_lshl_add_u64 v[6:7], v[4:5], 0, v[86:87]
	v_lshl_add_u64 v[8:9], v[2:3], 0, v[86:87]
	v_lshl_add_u64 v[12:13], v[4:5], 0, v[88:89]
	v_lshl_add_u64 v[16:17], v[2:3], 0, v[88:89]
	v_lshl_add_u64 v[20:21], v[4:5], 0, v[90:91]
	v_lshl_add_u64 v[24:25], v[2:3], 0, v[90:91]
	v_lshl_add_u64 v[28:29], v[4:5], 0, v[92:93]
	v_lshl_add_u64 v[2:3], v[2:3], 0, v[92:93]
	global_load_dwordx4 v[4:7], v[6:7], off
	s_nop 0
	global_load_dwordx4 v[8:11], v[8:9], off
	s_nop 0
	global_load_dwordx4 v[12:15], v[12:13], off
	s_nop 0
	global_load_dwordx4 v[16:19], v[16:17], off
	s_nop 0
	global_load_dwordx4 v[20:23], v[20:21], off
	s_nop 0
	global_load_dwordx4 v[24:27], v[24:25], off
	s_nop 0
	global_load_dwordx4 v[28:31], v[28:29], off
	s_nop 0
	global_load_dwordx4 v[32:35], v[2:3], off
	s_add_u32 s28, s90, s36
	s_addc_u32 s29, s91, 0
	v_mul_f32_e32 v2, 0x42800000, v1
	v_mul_f32_e32 v1, v1, v79
	s_add_u32 s24, s26, s36
	v_mul_f32_e32 v3, 0x3fb8aa3b, v1
	v_mul_f32_e32 v1, 0xbfb8aa3b, v1
	v_mul_f32_e32 v2, 0x3fb8aa3b, v2
	v_exp_f32_e32 v100, v3
	v_exp_f32_e32 v102, v1
	s_addc_u32 s25, s27, 0
	v_lshl_add_u64 v[98:99], v[80:81], 0, s[30:31]
	v_exp_f32_e32 v173, v2
	s_add_u32 s30, s47, s30
	s_addc_u32 s31, s48, 0
	v_cndmask_b32_e64 v96, v119, v117, s[22:23]
	v_lshl_add_u64 v[2:3], s[30:31], 0, v[144:145]
	v_add_u32_e32 v1, s45, v127
	v_cndmask_b32_e64 v104, v150, v124, s[22:23]
	v_cndmask_b32_e64 v108, v152, v139, s[22:23]
	v_cndmask_b32_e64 v110, v153, v141, s[22:23]
	v_cndmask_b32_e64 v112, v154, v143, s[22:23]
	v_ashrrev_i32_e32 v97, 31, v96
	v_add_u32_e32 v144, v37, v126
	v_ashrrev_i32_e32 v105, 31, v104
	v_lshl_add_u64 v[106:107], v[2:3], 0, v[82:83]
	v_ashrrev_i32_e32 v109, 31, v108
	v_ashrrev_i32_e32 v111, 31, v110
	v_ashrrev_i32_e32 v113, 31, v112
	v_lshl_add_u64 v[114:115], v[2:3], 0, v[84:85]
	v_add_u32_e32 v83, v1, v129
	v_add_u32_e32 v85, v1, v131
	v_add_u32_e32 v204, v1, v156
	v_add_u32_e32 v205, v1, v157
	v_add_u32_e32 v206, v1, v158
	v_add_u32_e32 v207, v1, v159
	v_add_u32_e32 v208, v1, v160
	v_add_u32_e32 v209, v1, v161
	v_mov_b32_e32 v103, v102
	v_mov_b32_e32 v101, v100
	s_mov_b32 s45, 0
	v_mov_b32_e32 v1, v0
	v_mov_b32_e32 v2, v0
	v_mov_b32_e32 v3, v0
	v_mov_b32_e32 v37, v0
	v_mov_b32_e32 v46, v0
	v_mov_b32_e32 v47, v0
	v_mov_b32_e32 v40, v0
	v_mov_b32_e32 v41, v0
	v_mov_b32_e32 v42, v0
	v_mov_b32_e32 v43, v0
	v_mov_b32_e32 v52, v0
	v_mov_b32_e32 v53, v0
	v_mov_b32_e32 v54, v0
	v_mov_b32_e32 v55, v0
	v_mov_b32_e32 v48, v0
	v_mov_b32_e32 v49, v0
	v_mov_b32_e32 v50, v0
	v_mov_b32_e32 v51, v0
	v_mov_b32_e32 v60, v0
	v_mov_b32_e32 v61, v0
	v_mov_b32_e32 v62, v0
	v_mov_b32_e32 v63, v0
	v_mov_b32_e32 v56, v0
	v_mov_b32_e32 v57, v0
	v_mov_b32_e32 v58, v0
	v_mov_b32_e32 v59, v0
	v_subrev_u32_e32 v95, s44, v94
	v_lshl_add_u32 v86, v95, 11, v86
	v_lshl_add_u32 v87, v95, 11, v88
	v_lshl_add_u32 v88, v95, 11, v90
	v_lshl_add_u32 v89, v95, 11, v92
	s_cmp_gt_u32 s45, 3
	s_cselect_b32 s30, 0x47, 3
	s_add_i32 s36, s30, s42
	s_and_b64 s[30:31], s[22:23], exec
	s_cselect_b32 s30, s45, s36
	s_lshl_b32 s30, s30, 6
	s_ashr_i32 s31, s30, 31
	s_add_u32 s30, s44, s30
	s_addc_u32 s31, s43, s31
	v_lshl_add_u64 v[94:95], s[30:31], 0, v[96:97]
	v_lshlrev_b64 v[94:95], 12, v[94:95]
	v_lshl_add_u64 v[94:95], v[98:99], 0, v[94:95]
	global_load_dwordx4 v[90:93], v[94:95], off
	s_branch .LBB0_71

; #define LAS __attribute__((address_space(3)))
; #define GAS __attribute__((address_space(1)))
; __device__ __forceinline__ bf16_t f2bf(float x) { return (bf16_t)(cvt_pk_bf16(x, x) & 0xffffu); }
; __device__ __forceinline__ float bf2f(bf16_t v) { return __uint_as_float((unsigned)v << 16); }
; __device__ __forceinline__ u32x4 pack8(const float* v) { u32x4 w; w.x = cvt_pk_bf16(v[0], v[1]); w.y = cvt_pk_bf16(v[2], v[3]); w.z = cvt_pk_bf16(v[4], v[5]); w.w = cvt_pk_bf16(v[6], v[7]); return w; }
; #define GLA_BAR() do { asm volatile("s_waitcnt lgkmcnt(0)" ::: "memory"); __builtin_amdgcn_s_barrier(); asm volatile("" ::: "memory"); } while (0)
; template <int DK, int DVS, bool RET> ...
;     ...
;     for (int step = 0; step < 68; ++step) {
;         const int cidx = dir ? (step < 4 ? 3 - step : 71 - step) : step;
;         const long R0 = (long)b * TB + cidx * 64;
;         GLA_BAR();
;         {
; #pragma unroll
;             for (int t = 0; t < TPW; ++t)
; #pragma unroll
;                 for (int j = 0; j < 4; ++j) STB[(tv * 16 + quad * 4 + j) * LK + (kt0 + t) * 16 + l16] = f2bf(st[t][j]);
;             { const int p = tid >> 3, vg = tid & 7; const long row = R0 + (dir ? 63 - p : p); vraw = *(const GAS vvec_t*)(Vg + row * ldv + vcol0 + vg * VPT); }
;             float bl;
;             if constexpr (RET) {
;                 static_assert(!RET || DK == 256, "retention prep: 64 x 256 = 2048 eight-wide items, four per thread");
;                 bl = 64.f * lg;
; #pragma unroll
;                 for (int j = 0; j < 4; ++j) { const int it = tid + 512 * j, p = it & 63, k0 = (it >> 6) * 8; const float bb = (float)(p + 1) * lg;
;                     const float eq = __expf(bb), ek = __expf(-bb); float a[8], c[8];
; #pragma unroll
;                     for (int e = 0; e < 8; ++e) { a[e] = bf2f((bf16_t)qv[j][e]) * eq; c[e] = bf2f((bf16_t)kv[j][e]) * ek; }
;                     *(LAS u32x4*)(QD + p * LK + k0) = pack8(a); *(LAS u32x4*)(KD + p * LK + k0) = pack8(c); }
.LBB0_71:
	v_cvt_pk_bf16_f32 v64, v56, s0
	s_add_i32 s39, s45, 1
	s_min_i32 s39, s39, 0x43
	s_cmp_gt_u32 s39, 3
	s_cselect_b32 s38, 0x47, 3
	s_sub_i32 s38, s38, s39
	s_and_b64 s[54:55], s[22:23], exec
	s_cselect_b32 s38, s39, s38
	s_lshl_b32 s38, s38, 6
	s_add_u32 s50, s44, s38
	s_addc_u32 s51, s43, 0
	s_lshl_b64 s[38:39], s[50:51], 11
	s_add_u32 s54, s24, s38
	s_addc_u32 s55, s25, s39
	s_add_u32 s38, s28, s38
	s_addc_u32 s39, s29, s39
	s_waitcnt lgkmcnt(0)
	s_barrier
	ds_write_b16 v210, v64
	v_cvt_pk_bf16_f32 v64, v57, s0
	ds_write_b16 v210, v64 offset:528
	v_cvt_pk_bf16_f32 v64, v58, s0
	ds_write_b16 v210, v64 offset:1056
	v_cvt_pk_bf16_f32 v64, v59, s0
	ds_write_b16 v210, v64 offset:1584
	v_cvt_pk_bf16_f32 v64, v60, s0
	ds_write_b16 v210, v64 offset:32
	v_cvt_pk_bf16_f32 v64, v61, s0
	ds_write_b16 v210, v64 offset:560
	v_cvt_pk_bf16_f32 v64, v62, s0
	ds_write_b16 v210, v64 offset:1088
	v_cvt_pk_bf16_f32 v64, v63, s0
	ds_write_b16 v210, v64 offset:1616
	v_cvt_pk_bf16_f32 v64, v48, s0
	ds_write_b16 v210, v64 offset:64
	v_cvt_pk_bf16_f32 v64, v49, s0
	ds_write_b16 v210, v64 offset:592
	v_cvt_pk_bf16_f32 v64, v50, s0
	ds_write_b16 v210, v64 offset:1120
	v_cvt_pk_bf16_f32 v64, v51, s0
	ds_write_b16 v210, v64 offset:1648
	v_cvt_pk_bf16_f32 v64, v52, s0
	ds_write_b16 v210, v64 offset:96
	v_cvt_pk_bf16_f32 v64, v53, s0
	ds_write_b16 v210, v64 offset:624
	v_cvt_pk_bf16_f32 v64, v54, s0
	ds_write_b16 v210, v64 offset:1152
	v_cvt_pk_bf16_f32 v64, v55, s0
	ds_write_b16 v210, v64 offset:1680
	v_cvt_pk_bf16_f32 v64, v40, s0
	ds_write_b16 v210, v64 offset:128
	v_cvt_pk_bf16_f32 v64, v41, s0
	ds_write_b16 v210, v64 offset:656
	v_cvt_pk_bf16_f32 v64, v42, s0
	ds_write_b16 v210, v64 offset:1184
	v_cvt_pk_bf16_f32 v64, v43, s0
	ds_write_b16 v210, v64 offset:1712
	v_cvt_pk_bf16_f32 v64, v44, s0
	ds_write_b16 v210, v64 offset:160
	v_cvt_pk_bf16_f32 v64, v45, s0
	ds_write_b16 v210, v64 offset:688
	v_cvt_pk_bf16_f32 v64, v46, s0
	s_cmp_gt_u32 s45, 3
	ds_write_b16 v210, v64 offset:1216
	v_cvt_pk_bf16_f32 v64, v47, s0
	s_cselect_b32 s30, 0x47, 3
	ds_write_b16 v210, v64 offset:1744
	v_cvt_pk_bf16_f32 v64, v36, s0
	s_add_i32 s36, s30, s42
	ds_write_b16 v210, v64 offset:192
	v_cvt_pk_bf16_f32 v64, v37, s0
	s_and_b64 s[30:31], s[22:23], exec
	ds_write_b16 v210, v64 offset:720
	v_cvt_pk_bf16_f32 v64, v38, s0
	s_cselect_b32 s30, s45, s36
	ds_write_b16 v210, v64 offset:1248
	v_cvt_pk_bf16_f32 v64, v39, s0
	s_lshl_b32 s30, s30, 6
	ds_write_b16 v210, v64 offset:1776
	v_cvt_pk_bf16_f32 v64, v0, s0
	s_ashr_i32 s31, s30, 31
	ds_write_b16 v210, v64 offset:224
	v_cvt_pk_bf16_f32 v64, v1, s0
	ds_write_b16 v210, v64 offset:752
	v_cvt_pk_bf16_f32 v64, v2, s0
	s_add_u32 s30, s44, s30
	ds_write_b16 v210, v64 offset:1280
	v_cvt_pk_bf16_f32 v64, v3, s0
	s_addc_u32 s31, s43, s31
	ds_write_b16 v210, v64 offset:1808
	s_waitcnt vmcnt(15)
	s_cmp_lg_u32 s45, 0
	s_cbranch_scc1 .Lret_w0
	s_waitcnt vmcnt(7)
.Lret_w0:
	v_and_b32_e32 v231, 0xffff0000, v8
	v_lshlrev_b32_e32 v230, 16, v8
	v_and_b32_e32 v229, 0xffff0000, v4
	v_lshlrev_b32_e32 v228, 16, v4
	v_pk_mul_f32 v[232:233], v[102:103], v[230:231]
	v_and_b32_e32 v231, 0xffff0000, v5
	v_lshlrev_b32_e32 v230, 16, v5
	v_and_b32_e32 v237, 0xffff0000, v6
	v_lshlrev_b32_e32 v236, 16, v6
	v_and_b32_e32 v241, 0xffff0000, v7
	v_lshlrev_b32_e32 v240, 16, v7
	v_pk_mul_f32 v[228:229], v[100:101], v[228:229]
	v_pk_mul_f32 v[230:231], v[100:101], v[230:231]
	v_and_b32_e32 v235, 0xffff0000, v9
	v_lshlrev_b32_e32 v234, 16, v9
	v_pk_mul_f32 v[236:237], v[100:101], v[236:237]
	v_and_b32_e32 v239, 0xffff0000, v10
	v_lshlrev_b32_e32 v238, 16, v10
	v_pk_mul_f32 v[240:241], v[100:101], v[240:241]
	v_and_b32_e32 v243, 0xffff0000, v11
	v_lshlrev_b32_e32 v242, 16, v11
	global_load_dwordx4 v[4:7], v86, s[38:39]
	global_load_dwordx4 v[8:11], v86, s[54:55]
	v_pk_mul_f32 v[234:235], v[102:103], v[234:235]
	v_pk_mul_f32 v[238:239], v[102:103], v[238:239]
	v_pk_mul_f32 v[242:243], v[102:103], v[242:243]
	v_cvt_pk_bf16_f32 v228, v228, v229
	v_cvt_pk_bf16_f32 v229, v230, v231
	v_cvt_pk_bf16_f32 v230, v236, v237
	v_cvt_pk_bf16_f32 v231, v240, v241
	ds_write_b128 v178, v[228:231]
	v_cvt_pk_bf16_f32 v228, v232, v233
	v_cvt_pk_bf16_f32 v229, v234, v235
	v_cvt_pk_bf16_f32 v230, v238, v239
	v_cvt_pk_bf16_f32 v231, v242, v243
	ds_write_b128 v179, v[228:231]
	s_waitcnt vmcnt(15)
	s_cmp_lg_u32 s45, 0
	s_cbranch_scc1 .Lret_w1
	s_waitcnt vmcnt(7)
; #define LAS __attribute__((address_space(3)))
; __device__ __forceinline__ bf16_t f2bf(float x) { return (bf16_t)(cvt_pk_bf16(x, x) & 0xffffu); }
; __device__ __forceinline__ float bf2f(bf16_t v) { return __uint_as_float((unsigned)v << 16); }
; __device__ __forceinline__ u32x4 pack8(const float* v) { u32x4 w; w.x = cvt_pk_bf16(v[0], v[1]); w.y = cvt_pk_bf16(v[2], v[3]); w.z = cvt_pk_bf16(v[4], v[5]); w.w = cvt_pk_bf16(v[6], v[7]); return w; }
; #define GLA_BAR() do { asm volatile("s_waitcnt lgkmcnt(0)" ::: "memory"); __builtin_amdgcn_s_barrier(); asm volatile("" ::: "memory"); } while (0)
; template <int DK, int DVS, bool RET> ...
;     ...
;                 for (int j = 0; j < 4; ++j) { const int it = tid + 512 * j, p = it & 63, k0 = (it >> 6) * 8; const float bb = (float)(p + 1) * lg;
;                     const float eq = __expf(bb), ek = __expf(-bb); float a[8], c[8];
; #pragma unroll
;                     for (int e = 0; e < 8; ++e) { a[e] = bf2f((bf16_t)qv[j][e]) * eq; c[e] = bf2f((bf16_t)kv[j][e]) * ek; }
;                     *(LAS u32x4*)(QD + p * LK + k0) = pack8(a); *(LAS u32x4*)(KD + p * LK + k0) = pack8(c); }
;             } else {
;                 float c = 0.f;
; #pragma unroll
;                 for (int i = 0; i < PPT; ++i) c += lc[i];
;                 TOT[pg * 128 + kx] = c;
;                 GLA_BAR();
;                 float off = 0.f; bl = 0.f;
; #pragma unroll
;                 for (int g = 0; g < NPG; ++g) { const float t = TOT[g * 128 + kx]; if (g < pg) off += t; bl += t; }
;                 float bb = off;
; #pragma unroll
;                 for (int i = 0; i < PPT; ++i) { const int p = pg * PPT + i;
;                     const float qf = bf2f(qr[i]), kf = 1.f - __expf(lc[i]); bb += lc[i];
;                     QD[p * LK + kx] = f2bf(qf * __expf(bb)); KD[p * LK + kx] = f2bf(kf * __expf(-bb)); }
;             }
;             if (pg == 0) EL[kx] = __expf(bl);
;             { const int p = tid >> 3, vg = tid & 7; *(LAS vvec_t*)(VI + p * LV + vg * VPT) = vraw; }
;         }
;         if (step + 1 < 68) GLA_LOAD(step + 1);
.Lret_w1:
	v_and_b32_e32 v231, 0xffff0000, v16
	v_lshlrev_b32_e32 v230, 16, v16
	v_and_b32_e32 v229, 0xffff0000, v12
	v_lshlrev_b32_e32 v228, 16, v12
	v_pk_mul_f32 v[232:233], v[102:103], v[230:231]
	v_and_b32_e32 v231, 0xffff0000, v13
	v_lshlrev_b32_e32 v230, 16, v13
	v_and_b32_e32 v237, 0xffff0000, v14
	v_lshlrev_b32_e32 v236, 16, v14
	v_and_b32_e32 v241, 0xffff0000, v15
	v_lshlrev_b32_e32 v240, 16, v15
	v_pk_mul_f32 v[228:229], v[100:101], v[228:229]
	v_pk_mul_f32 v[230:231], v[100:101], v[230:231]
	v_and_b32_e32 v235, 0xffff0000, v17
	v_lshlrev_b32_e32 v234, 16, v17
	v_pk_mul_f32 v[236:237], v[100:101], v[236:237]
	v_and_b32_e32 v239, 0xffff0000, v18
	v_lshlrev_b32_e32 v238, 16, v18
	v_pk_mul_f32 v[240:241], v[100:101], v[240:241]
	v_and_b32_e32 v243, 0xffff0000, v19
	v_lshlrev_b32_e32 v242, 16, v19
	global_load_dwordx4 v[12:15], v87, s[38:39]
	global_load_dwordx4 v[16:19], v87, s[54:55]
	v_pk_mul_f32 v[234:235], v[102:103], v[234:235]
	v_pk_mul_f32 v[238:239], v[102:103], v[238:239]
	v_pk_mul_f32 v[242:243], v[102:103], v[242:243]
	v_cvt_pk_bf16_f32 v228, v228, v229
	v_cvt_pk_bf16_f32 v229, v230, v231
	v_cvt_pk_bf16_f32 v230, v236, v237
	v_cvt_pk_bf16_f32 v231, v240, v241
	ds_write_b128 v180, v[228:231]
	v_cvt_pk_bf16_f32 v228, v232, v233
	v_cvt_pk_bf16_f32 v229, v234, v235
	v_cvt_pk_bf16_f32 v230, v238, v239
	v_cvt_pk_bf16_f32 v231, v242, v243
	ds_write_b128 v181, v[228:231]
	s_waitcnt vmcnt(15)
	s_cmp_lg_u32 s45, 0
	s_cbranch_scc1 .Lret_w2
	s_waitcnt vmcnt(7)
.Lret_w2:
	v_and_b32_e32 v231, 0xffff0000, v24
	v_lshlrev_b32_e32 v230, 16, v24
	v_and_b32_e32 v229, 0xffff0000, v20
	v_lshlrev_b32_e32 v228, 16, v20
	v_pk_mul_f32 v[232:233], v[102:103], v[230:231]
	v_and_b32_e32 v231, 0xffff0000, v21
	v_lshlrev_b32_e32 v230, 16, v21
	v_and_b32_e32 v237, 0xffff0000, v22
	v_lshlrev_b32_e32 v236, 16, v22
	v_and_b32_e32 v241, 0xffff0000, v23
	v_lshlrev_b32_e32 v240, 16, v23
	v_pk_mul_f32 v[228:229], v[100:101], v[228:229]
	v_pk_mul_f32 v[230:231], v[100:101], v[230:231]
	v_and_b32_e32 v235, 0xffff0000, v25
	v_lshlrev_b32_e32 v234, 16, v25
	v_pk_mul_f32 v[236:237], v[100:101], v[236:237]
	v_and_b32_e32 v239, 0xffff0000, v26
	v_lshlrev_b32_e32 v238, 16, v26
	v_pk_mul_f32 v[240:241], v[100:101], v[240:241]
	v_and_b32_e32 v243, 0xffff0000, v27
	v_lshlrev_b32_e32 v242, 16, v27
	global_load_dwordx4 v[20:23], v88, s[38:39]
	global_load_dwordx4 v[24:27], v88, s[54:55]
	v_pk_mul_f32 v[234:235], v[102:103], v[234:235]
	v_pk_mul_f32 v[238:239], v[102:103], v[238:239]
	v_pk_mul_f32 v[242:243], v[102:103], v[242:243]
	v_cvt_pk_bf16_f32 v228, v228, v229
	v_cvt_pk_bf16_f32 v229, v230, v231
	v_cvt_pk_bf16_f32 v230, v236, v237
	v_cvt_pk_bf16_f32 v231, v240, v241
	ds_write_b128 v182, v[228:231]
	v_cvt_pk_bf16_f32 v228, v232, v233
	v_cvt_pk_bf16_f32 v229, v234, v235
	v_cvt_pk_bf16_f32 v230, v238, v239
	v_cvt_pk_bf16_f32 v231, v242, v243
	ds_write_b128 v183, v[228:231]
	s_waitcnt vmcnt(15)
	s_cmp_lg_u32 s45, 0
	s_cbranch_scc1 .Lret_w3
	s_waitcnt vmcnt(7)
.Lret_w3:
	v_and_b32_e32 v231, 0xffff0000, v32
	v_lshlrev_b32_e32 v230, 16, v32
	v_and_b32_e32 v229, 0xffff0000, v28
	v_lshlrev_b32_e32 v228, 16, v28
	v_pk_mul_f32 v[232:233], v[102:103], v[230:231]
	v_and_b32_e32 v231, 0xffff0000, v29
	v_lshlrev_b32_e32 v230, 16, v29
	v_and_b32_e32 v237, 0xffff0000, v30
	v_lshlrev_b32_e32 v236, 16, v30
	v_and_b32_e32 v241, 0xffff0000, v31
	v_lshlrev_b32_e32 v240, 16, v31
	v_pk_mul_f32 v[228:229], v[100:101], v[228:229]
	v_pk_mul_f32 v[230:231], v[100:101], v[230:231]
	v_and_b32_e32 v235, 0xffff0000, v33
	v_lshlrev_b32_e32 v234, 16, v33
	v_pk_mul_f32 v[236:237], v[100:101], v[236:237]
	v_and_b32_e32 v239, 0xffff0000, v34
	v_lshlrev_b32_e32 v238, 16, v34
	v_pk_mul_f32 v[240:241], v[100:101], v[240:241]
	v_and_b32_e32 v243, 0xffff0000, v35
	v_lshlrev_b32_e32 v242, 16, v35
	global_load_dwordx4 v[28:31], v89, s[38:39]
	global_load_dwordx4 v[32:35], v89, s[54:55]
	v_pk_mul_f32 v[234:235], v[102:103], v[234:235]
	v_pk_mul_f32 v[238:239], v[102:103], v[238:239]
	v_pk_mul_f32 v[242:243], v[102:103], v[242:243]
	v_cvt_pk_bf16_f32 v228, v228, v229
	v_cvt_pk_bf16_f32 v229, v230, v231
	v_cvt_pk_bf16_f32 v230, v236, v237
	v_cvt_pk_bf16_f32 v231, v240, v241
	ds_write_b128 v184, v[228:231]
	v_cvt_pk_bf16_f32 v228, v232, v233
	v_cvt_pk_bf16_f32 v229, v234, v235
	v_cvt_pk_bf16_f32 v230, v238, v239
	v_cvt_pk_bf16_f32 v231, v242, v243
	ds_write_b128 v185, v[228:231]
	s_and_saveexec_b64 s[40:41], vcc
	ds_write_b32 v171, v173
	s_or_b64 exec, exec, s[40:41]
	s_add_i32 s36, s45, 1
	s_cmpk_eq_i32 s42, 0xffbd
	s_waitcnt vmcnt(16)
	s_cmp_lg_u32 s45, 0
	s_cbranch_scc1 .Lret_w4
	s_waitcnt vmcnt(8)
.Lret_w4:
	ds_write_b128 v172, v[90:93]
	s_nop 1
	v_lshl_add_u64 v[94:95], s[50:51], 0, v[96:97]
	v_lshlrev_b64 v[94:95], 12, v[94:95]
	v_lshl_add_u64 v[94:95], v[98:99], 0, v[94:95]
	global_load_dwordx4 v[90:93], v[94:95], off
	s_branch .LBB0_70
